# adaLN modulation GEMV: all weight loads issued up front, one silu per lane broadcast by readlane (on top of combo1)
# speedup vs baseline: 1.0041x; 1.0041x over previous
; __device__ __forceinline__ float siluf(float x) { return x * sigmf(x); }
; __device__ __forceinline__ void prologue_phase(const Args& a, LAS unsigned char* lds, int G) {
;     ...
;         for (int it = blockIdx.x; it < 192; it += G) {
;             const int half = it / 96, r = it % 96, l = r / 48, cgp = r % 48, col = cgp * 64 + lane, kb = half * 512 + wave * 64;
;             const float* wp = ada_w + (size_t)l * D * 3072 + (size_t)kb * 3072 + col;
;             float wv[64];
; #pragma unroll
;             for (int k = 0; k < 64; ++k) wv[k] = wp[(size_t)k * 3072];
;             float a0 = 0.f, a1 = 0.f;
; #pragma unroll
;             for (int k = 0; k < 64; ++k) { const float c0 = cvec[kb + k], c1 = cvec[D + kb + k]; a0 += siluf(c0) * wv[k]; a1 += siluf(c1) * wv[k]; }
.LBB0_23:
	s_mul_hi_i32 s4, s93, 0x2aaaaaab
	s_lshr_b32 s5, s4, 31
	s_ashr_i32 s4, s4, 4
	s_add_i32 s95, s4, s5
	s_mul_i32 s4, s95, 0xffffffa0
	s_add_i32 s4, s93, s4
	s_mul_i32 s5, s4, 43
	s_sext_i32_i16 s94, s5
	s_ashr_i32 s94, s94, 11
	s_bfe_u32 s5, s5, 0x1000f
	s_add_i32 s5, s94, s5
	s_mul_i32 s94, s5, 48
	s_sub_i32 s96, s4, s94
	s_sext_i32_i16 s94, s5
	s_mul_i32 s4, s94, 0x300000
	s_ashr_i32 s5, s4, 31
	s_lshl_b64 s[4:5], s[4:5], 2
	s_add_u32 s4, s74, s4
	s_addc_u32 s5, s75, s5
	v_mov_b64_e32 v[0:1], s[4:5]
	s_sext_i32_i8 s4, s96
	v_lshl_or_b32 v36, s4, 6, v130
	v_lshl_add_u32 v16, s95, 9, v132
	v_mad_i64_i32 v[0:1], s[4:5], v16, s24, v[0:1]
	v_ashrrev_i32_e32 v37, 31, v36
	v_lshl_add_u64 v[0:1], v[36:37], 2, v[0:1]
	v_add_lshl_u32 v8, v16, v130, 2
	v_add_u32_e32 v9, 0x1000, v8
	global_load_dword v60, v8, s[70:71]
	global_load_dword v61, v9, s[70:71]
	s_mov_b64 s[98:99], 0x3000
	v_mov_b32_e32 v44, 0
	v_mov_b32_e32 v46, 0
	global_load_dword v64, v[0:1], off
	v_lshl_add_u64 v[6:7], v[0:1], 0, s[98:99]
	global_load_dword v65, v[6:7], off
	v_lshl_add_u64 v[6:7], v[6:7], 0, s[98:99]
	global_load_dword v66, v[6:7], off
	v_lshl_add_u64 v[6:7], v[6:7], 0, s[98:99]
	global_load_dword v67, v[6:7], off
	v_lshl_add_u64 v[6:7], v[6:7], 0, s[98:99]
	global_load_dword v68, v[6:7], off
	v_lshl_add_u64 v[6:7], v[6:7], 0, s[98:99]
	global_load_dword v69, v[6:7], off
	v_lshl_add_u64 v[6:7], v[6:7], 0, s[98:99]
	global_load_dword v70, v[6:7], off
	v_lshl_add_u64 v[6:7], v[6:7], 0, s[98:99]
	global_load_dword v71, v[6:7], off
	v_lshl_add_u64 v[6:7], v[6:7], 0, s[98:99]
	global_load_dword v72, v[6:7], off
	v_lshl_add_u64 v[6:7], v[6:7], 0, s[98:99]
	global_load_dword v73, v[6:7], off
	v_lshl_add_u64 v[6:7], v[6:7], 0, s[98:99]
	global_load_dword v74, v[6:7], off
	v_lshl_add_u64 v[6:7], v[6:7], 0, s[98:99]
	global_load_dword v75, v[6:7], off
	v_lshl_add_u64 v[6:7], v[6:7], 0, s[98:99]
	global_load_dword v76, v[6:7], off
	v_lshl_add_u64 v[6:7], v[6:7], 0, s[98:99]
	global_load_dword v77, v[6:7], off
	v_lshl_add_u64 v[6:7], v[6:7], 0, s[98:99]
	global_load_dword v78, v[6:7], off
	v_lshl_add_u64 v[6:7], v[6:7], 0, s[98:99]
	global_load_dword v79, v[6:7], off
	v_lshl_add_u64 v[6:7], v[6:7], 0, s[98:99]
	global_load_dword v80, v[6:7], off
	v_lshl_add_u64 v[6:7], v[6:7], 0, s[98:99]
	global_load_dword v81, v[6:7], off
	v_lshl_add_u64 v[6:7], v[6:7], 0, s[98:99]
	global_load_dword v82, v[6:7], off
	v_lshl_add_u64 v[6:7], v[6:7], 0, s[98:99]
	global_load_dword v83, v[6:7], off
	v_lshl_add_u64 v[6:7], v[6:7], 0, s[98:99]
	global_load_dword v84, v[6:7], off
	v_lshl_add_u64 v[6:7], v[6:7], 0, s[98:99]
	global_load_dword v85, v[6:7], off
	v_lshl_add_u64 v[6:7], v[6:7], 0, s[98:99]
	global_load_dword v86, v[6:7], off
	v_lshl_add_u64 v[6:7], v[6:7], 0, s[98:99]
	global_load_dword v87, v[6:7], off
	v_lshl_add_u64 v[6:7], v[6:7], 0, s[98:99]
	global_load_dword v88, v[6:7], off
	v_lshl_add_u64 v[6:7], v[6:7], 0, s[98:99]
	global_load_dword v89, v[6:7], off
	v_lshl_add_u64 v[6:7], v[6:7], 0, s[98:99]
	global_load_dword v90, v[6:7], off
	v_lshl_add_u64 v[6:7], v[6:7], 0, s[98:99]
	global_load_dword v91, v[6:7], off
	v_lshl_add_u64 v[6:7], v[6:7], 0, s[98:99]
	global_load_dword v92, v[6:7], off
	v_lshl_add_u64 v[6:7], v[6:7], 0, s[98:99]
	global_load_dword v93, v[6:7], off
	v_lshl_add_u64 v[6:7], v[6:7], 0, s[98:99]
	global_load_dword v94, v[6:7], off
	v_lshl_add_u64 v[6:7], v[6:7], 0, s[98:99]
	global_load_dword v95, v[6:7], off
	v_lshl_add_u64 v[6:7], v[6:7], 0, s[98:99]
	global_load_dword v96, v[6:7], off
	v_lshl_add_u64 v[6:7], v[6:7], 0, s[98:99]
	global_load_dword v97, v[6:7], off
	v_lshl_add_u64 v[6:7], v[6:7], 0, s[98:99]
	global_load_dword v98, v[6:7], off
	v_lshl_add_u64 v[6:7], v[6:7], 0, s[98:99]
	global_load_dword v99, v[6:7], off
	v_lshl_add_u64 v[6:7], v[6:7], 0, s[98:99]
	global_load_dword v100, v[6:7], off
	v_lshl_add_u64 v[6:7], v[6:7], 0, s[98:99]
	global_load_dword v101, v[6:7], off
	v_lshl_add_u64 v[6:7], v[6:7], 0, s[98:99]
	global_load_dword v102, v[6:7], off
	v_lshl_add_u64 v[6:7], v[6:7], 0, s[98:99]
	global_load_dword v103, v[6:7], off
	v_lshl_add_u64 v[6:7], v[6:7], 0, s[98:99]
	global_load_dword v104, v[6:7], off
	v_lshl_add_u64 v[6:7], v[6:7], 0, s[98:99]
	global_load_dword v105, v[6:7], off
	v_lshl_add_u64 v[6:7], v[6:7], 0, s[98:99]
	global_load_dword v106, v[6:7], off
	v_lshl_add_u64 v[6:7], v[6:7], 0, s[98:99]
	global_load_dword v107, v[6:7], off
	v_lshl_add_u64 v[6:7], v[6:7], 0, s[98:99]
	s_waitcnt vmcnt(44)
	v_mul_f32_e32 v10, 0xbfb8aa3b, v60
	v_mul_f32_e32 v11, 0xbfb8aa3b, v61
	v_exp_f32_e32 v10, v10
	v_exp_f32_e32 v11, v11
	s_nop 0
	v_add_f32_e32 v10, 1.0, v10
	v_add_f32_e32 v11, 1.0, v11
	v_rcp_f32_e32 v10, v10
	v_rcp_f32_e32 v11, v11
	s_nop 0
	v_mul_f32_e32 v60, v60, v10
	v_mul_f32_e32 v61, v61, v11
	global_load_dword v108, v[6:7], off
	v_lshl_add_u64 v[6:7], v[6:7], 0, s[98:99]
	global_load_dword v109, v[6:7], off
	v_lshl_add_u64 v[6:7], v[6:7], 0, s[98:99]
	global_load_dword v110, v[6:7], off
	v_lshl_add_u64 v[6:7], v[6:7], 0, s[98:99]
	global_load_dword v111, v[6:7], off
	v_lshl_add_u64 v[6:7], v[6:7], 0, s[98:99]
	global_load_dword v112, v[6:7], off
	v_lshl_add_u64 v[6:7], v[6:7], 0, s[98:99]
	global_load_dword v113, v[6:7], off
	v_lshl_add_u64 v[6:7], v[6:7], 0, s[98:99]
	global_load_dword v114, v[6:7], off
	v_lshl_add_u64 v[6:7], v[6:7], 0, s[98:99]
	global_load_dword v115, v[6:7], off
	v_lshl_add_u64 v[6:7], v[6:7], 0, s[98:99]
	global_load_dword v116, v[6:7], off
	v_lshl_add_u64 v[6:7], v[6:7], 0, s[98:99]
	global_load_dword v117, v[6:7], off
	v_lshl_add_u64 v[6:7], v[6:7], 0, s[98:99]
	global_load_dword v118, v[6:7], off
	v_lshl_add_u64 v[6:7], v[6:7], 0, s[98:99]
	global_load_dword v119, v[6:7], off
	v_lshl_add_u64 v[6:7], v[6:7], 0, s[98:99]
	global_load_dword v120, v[6:7], off
	v_lshl_add_u64 v[6:7], v[6:7], 0, s[98:99]
	global_load_dword v121, v[6:7], off
	v_lshl_add_u64 v[6:7], v[6:7], 0, s[98:99]
	global_load_dword v122, v[6:7], off
	v_lshl_add_u64 v[6:7], v[6:7], 0, s[98:99]
	global_load_dword v123, v[6:7], off
	v_lshl_add_u64 v[6:7], v[6:7], 0, s[98:99]
	global_load_dword v124, v[6:7], off
	v_lshl_add_u64 v[6:7], v[6:7], 0, s[98:99]
	global_load_dword v125, v[6:7], off
	v_lshl_add_u64 v[6:7], v[6:7], 0, s[98:99]
	global_load_dword v126, v[6:7], off
	v_lshl_add_u64 v[6:7], v[6:7], 0, s[98:99]
	global_load_dword v127, v[6:7], off
	v_readlane_b32 s4, v60, 0
	v_readlane_b32 s5, v61, 0
	v_readlane_b32 s98, v60, 1
	v_readlane_b32 s99, v61, 1
	v_readlane_b32 s100, v60, 2
	v_readlane_b32 s101, v61, 2
	s_waitcnt vmcnt(48)
; __device__ __forceinline__ float siluf(float x) { return x * sigmf(x); }
; __device__ __forceinline__ void prologue_phase(const Args& a, LAS unsigned char* lds, int G) {
;     ...
;             float a0 = 0.f, a1 = 0.f;
; #pragma unroll
;             for (int k = 0; k < 64; ++k) { const float c0 = cvec[kb + k], c1 = cvec[D + kb + k]; a0 += siluf(c0) * wv[k]; a1 += siluf(c1) * wv[k]; }
	v_fmac_f32_e32 v44, s4, v64
	v_fmac_f32_e32 v46, s5, v64
	v_readlane_b32 s4, v60, 3
	v_readlane_b32 s5, v61, 3
	v_fmac_f32_e32 v44, s98, v65
	v_fmac_f32_e32 v46, s99, v65
	v_readlane_b32 s98, v60, 4
	v_readlane_b32 s99, v61, 4
	v_fmac_f32_e32 v44, s100, v66
	v_fmac_f32_e32 v46, s101, v66
	v_readlane_b32 s100, v60, 5
	v_readlane_b32 s101, v61, 5
	v_fmac_f32_e32 v44, s4, v67
	v_fmac_f32_e32 v46, s5, v67
	v_readlane_b32 s4, v60, 6
	v_readlane_b32 s5, v61, 6
	v_fmac_f32_e32 v44, s98, v68
	v_fmac_f32_e32 v46, s99, v68
	v_readlane_b32 s98, v60, 7
	v_readlane_b32 s99, v61, 7
	v_fmac_f32_e32 v44, s100, v69
	v_fmac_f32_e32 v46, s101, v69
	v_readlane_b32 s100, v60, 8
	v_readlane_b32 s101, v61, 8
	v_fmac_f32_e32 v44, s4, v70
	v_fmac_f32_e32 v46, s5, v70
	v_readlane_b32 s4, v60, 9
	v_readlane_b32 s5, v61, 9
	v_fmac_f32_e32 v44, s98, v71
	v_fmac_f32_e32 v46, s99, v71
	v_readlane_b32 s98, v60, 10
	v_readlane_b32 s99, v61, 10
	v_fmac_f32_e32 v44, s100, v72
	v_fmac_f32_e32 v46, s101, v72
	v_readlane_b32 s100, v60, 11
	v_readlane_b32 s101, v61, 11
	v_fmac_f32_e32 v44, s4, v73
	v_fmac_f32_e32 v46, s5, v73
	v_readlane_b32 s4, v60, 12
	v_readlane_b32 s5, v61, 12
	v_fmac_f32_e32 v44, s98, v74
	v_fmac_f32_e32 v46, s99, v74
	v_readlane_b32 s98, v60, 13
	v_readlane_b32 s99, v61, 13
	v_fmac_f32_e32 v44, s100, v75
	v_fmac_f32_e32 v46, s101, v75
	v_readlane_b32 s100, v60, 14
	v_readlane_b32 s101, v61, 14
	v_fmac_f32_e32 v44, s4, v76
	v_fmac_f32_e32 v46, s5, v76
	v_readlane_b32 s4, v60, 15
	v_readlane_b32 s5, v61, 15
	v_fmac_f32_e32 v44, s98, v77
	v_fmac_f32_e32 v46, s99, v77
	v_readlane_b32 s98, v60, 16
	v_readlane_b32 s99, v61, 16
	v_fmac_f32_e32 v44, s100, v78
	v_fmac_f32_e32 v46, s101, v78
	v_readlane_b32 s100, v60, 17
	v_readlane_b32 s101, v61, 17
	v_fmac_f32_e32 v44, s4, v79
	v_fmac_f32_e32 v46, s5, v79
	v_readlane_b32 s4, v60, 18
	v_readlane_b32 s5, v61, 18
	s_waitcnt vmcnt(32)
	v_fmac_f32_e32 v44, s98, v80
	v_fmac_f32_e32 v46, s99, v80
	v_readlane_b32 s98, v60, 19
	v_readlane_b32 s99, v61, 19
	v_fmac_f32_e32 v44, s100, v81
	v_fmac_f32_e32 v46, s101, v81
	v_readlane_b32 s100, v60, 20
	v_readlane_b32 s101, v61, 20
	v_fmac_f32_e32 v44, s4, v82
	v_fmac_f32_e32 v46, s5, v82
	v_readlane_b32 s4, v60, 21
	v_readlane_b32 s5, v61, 21
	v_fmac_f32_e32 v44, s98, v83
	v_fmac_f32_e32 v46, s99, v83
	v_readlane_b32 s98, v60, 22
	v_readlane_b32 s99, v61, 22
	v_fmac_f32_e32 v44, s100, v84
	v_fmac_f32_e32 v46, s101, v84
	v_readlane_b32 s100, v60, 23
	v_readlane_b32 s101, v61, 23
	v_fmac_f32_e32 v44, s4, v85
	v_fmac_f32_e32 v46, s5, v85
	v_readlane_b32 s4, v60, 24
	v_readlane_b32 s5, v61, 24
	v_fmac_f32_e32 v44, s98, v86
	v_fmac_f32_e32 v46, s99, v86
	v_readlane_b32 s98, v60, 25
	v_readlane_b32 s99, v61, 25
	v_fmac_f32_e32 v44, s100, v87
	v_fmac_f32_e32 v46, s101, v87
	v_readlane_b32 s100, v60, 26
	v_readlane_b32 s101, v61, 26
	v_fmac_f32_e32 v44, s4, v88
	v_fmac_f32_e32 v46, s5, v88
	v_readlane_b32 s4, v60, 27
	v_readlane_b32 s5, v61, 27
	v_fmac_f32_e32 v44, s98, v89
	v_fmac_f32_e32 v46, s99, v89
	v_readlane_b32 s98, v60, 28
	v_readlane_b32 s99, v61, 28
	v_fmac_f32_e32 v44, s100, v90
	v_fmac_f32_e32 v46, s101, v90
	v_readlane_b32 s100, v60, 29
	v_readlane_b32 s101, v61, 29
	v_fmac_f32_e32 v44, s4, v91
	v_fmac_f32_e32 v46, s5, v91
	v_readlane_b32 s4, v60, 30
	v_readlane_b32 s5, v61, 30
	v_fmac_f32_e32 v44, s98, v92
	v_fmac_f32_e32 v46, s99, v92
	v_readlane_b32 s98, v60, 31
	v_readlane_b32 s99, v61, 31
	v_fmac_f32_e32 v44, s100, v93
	v_fmac_f32_e32 v46, s101, v93
	v_readlane_b32 s100, v60, 32
	v_readlane_b32 s101, v61, 32
	v_fmac_f32_e32 v44, s4, v94
	v_fmac_f32_e32 v46, s5, v94
	v_readlane_b32 s4, v60, 33
	v_readlane_b32 s5, v61, 33
	v_fmac_f32_e32 v44, s98, v95
	v_fmac_f32_e32 v46, s99, v95
	v_readlane_b32 s98, v60, 34
	v_readlane_b32 s99, v61, 34
	s_waitcnt vmcnt(16)
; __device__ __forceinline__ float siluf(float x) { return x * sigmf(x); }
; __device__ __forceinline__ void prologue_phase(const Args& a, LAS unsigned char* lds, int G) {
;     ...
;             for (int k = 0; k < 64; ++k) { const float c0 = cvec[kb + k], c1 = cvec[D + kb + k]; a0 += siluf(c0) * wv[k]; a1 += siluf(c1) * wv[k]; }
;             red[(wave * 2 + 0) * 64 + lane] = a0; red[(wave * 2 + 1) * 64 + lane] = a1;
;             __syncthreads();
;             if (wave < 2) { float s = half == 0 ? ada_b[l * 3072 + col] : 0.f;
	v_fmac_f32_e32 v44, s100, v96
	v_fmac_f32_e32 v46, s101, v96
	v_readlane_b32 s100, v60, 35
	v_readlane_b32 s101, v61, 35
	v_fmac_f32_e32 v44, s4, v97
	v_fmac_f32_e32 v46, s5, v97
	v_readlane_b32 s4, v60, 36
	v_readlane_b32 s5, v61, 36
	v_fmac_f32_e32 v44, s98, v98
	v_fmac_f32_e32 v46, s99, v98
	v_readlane_b32 s98, v60, 37
	v_readlane_b32 s99, v61, 37
	v_fmac_f32_e32 v44, s100, v99
	v_fmac_f32_e32 v46, s101, v99
	v_readlane_b32 s100, v60, 38
	v_readlane_b32 s101, v61, 38
	v_fmac_f32_e32 v44, s4, v100
	v_fmac_f32_e32 v46, s5, v100
	v_readlane_b32 s4, v60, 39
	v_readlane_b32 s5, v61, 39
	v_fmac_f32_e32 v44, s98, v101
	v_fmac_f32_e32 v46, s99, v101
	v_readlane_b32 s98, v60, 40
	v_readlane_b32 s99, v61, 40
	v_fmac_f32_e32 v44, s100, v102
	v_fmac_f32_e32 v46, s101, v102
	v_readlane_b32 s100, v60, 41
	v_readlane_b32 s101, v61, 41
	v_fmac_f32_e32 v44, s4, v103
	v_fmac_f32_e32 v46, s5, v103
	v_readlane_b32 s4, v60, 42
	v_readlane_b32 s5, v61, 42
	v_fmac_f32_e32 v44, s98, v104
	v_fmac_f32_e32 v46, s99, v104
	v_readlane_b32 s98, v60, 43
	v_readlane_b32 s99, v61, 43
	v_fmac_f32_e32 v44, s100, v105
	v_fmac_f32_e32 v46, s101, v105
	v_readlane_b32 s100, v60, 44
	v_readlane_b32 s101, v61, 44
	v_fmac_f32_e32 v44, s4, v106
	v_fmac_f32_e32 v46, s5, v106
	v_readlane_b32 s4, v60, 45
	v_readlane_b32 s5, v61, 45
	v_fmac_f32_e32 v44, s98, v107
	v_fmac_f32_e32 v46, s99, v107
	v_readlane_b32 s98, v60, 46
	v_readlane_b32 s99, v61, 46
	v_fmac_f32_e32 v44, s100, v108
	v_fmac_f32_e32 v46, s101, v108
	v_readlane_b32 s100, v60, 47
	v_readlane_b32 s101, v61, 47
	v_fmac_f32_e32 v44, s4, v109
	v_fmac_f32_e32 v46, s5, v109
	v_readlane_b32 s4, v60, 48
	v_readlane_b32 s5, v61, 48
	v_fmac_f32_e32 v44, s98, v110
	v_fmac_f32_e32 v46, s99, v110
	v_readlane_b32 s98, v60, 49
	v_readlane_b32 s99, v61, 49
	v_fmac_f32_e32 v44, s100, v111
	v_fmac_f32_e32 v46, s101, v111
	v_readlane_b32 s100, v60, 50
	v_readlane_b32 s101, v61, 50
	s_waitcnt vmcnt(0)
	v_fmac_f32_e32 v44, s4, v112
	v_fmac_f32_e32 v46, s5, v112
	v_readlane_b32 s4, v60, 51
	v_readlane_b32 s5, v61, 51
	v_fmac_f32_e32 v44, s98, v113
	v_fmac_f32_e32 v46, s99, v113
	v_readlane_b32 s98, v60, 52
	v_readlane_b32 s99, v61, 52
	v_fmac_f32_e32 v44, s100, v114
	v_fmac_f32_e32 v46, s101, v114
	v_readlane_b32 s100, v60, 53
	v_readlane_b32 s101, v61, 53
	v_fmac_f32_e32 v44, s4, v115
	v_fmac_f32_e32 v46, s5, v115
	v_readlane_b32 s4, v60, 54
	v_readlane_b32 s5, v61, 54
	v_fmac_f32_e32 v44, s98, v116
	v_fmac_f32_e32 v46, s99, v116
	v_readlane_b32 s98, v60, 55
	v_readlane_b32 s99, v61, 55
	v_fmac_f32_e32 v44, s100, v117
	v_fmac_f32_e32 v46, s101, v117
	v_readlane_b32 s100, v60, 56
	v_readlane_b32 s101, v61, 56
	v_fmac_f32_e32 v44, s4, v118
	v_fmac_f32_e32 v46, s5, v118
	v_readlane_b32 s4, v60, 57
	v_readlane_b32 s5, v61, 57
	v_fmac_f32_e32 v44, s98, v119
	v_fmac_f32_e32 v46, s99, v119
	v_readlane_b32 s98, v60, 58
	v_readlane_b32 s99, v61, 58
	v_fmac_f32_e32 v44, s100, v120
	v_fmac_f32_e32 v46, s101, v120
	v_readlane_b32 s100, v60, 59
	v_readlane_b32 s101, v61, 59
	v_fmac_f32_e32 v44, s4, v121
	v_fmac_f32_e32 v46, s5, v121
	v_readlane_b32 s4, v60, 60
	v_readlane_b32 s5, v61, 60
	v_fmac_f32_e32 v44, s98, v122
	v_fmac_f32_e32 v46, s99, v122
	v_readlane_b32 s98, v60, 61
	v_readlane_b32 s99, v61, 61
	v_fmac_f32_e32 v44, s100, v123
	v_fmac_f32_e32 v46, s101, v123
	v_readlane_b32 s100, v60, 62
	v_readlane_b32 s101, v61, 62
	v_fmac_f32_e32 v44, s4, v124
	v_fmac_f32_e32 v46, s5, v124
	v_readlane_b32 s4, v60, 63
	v_readlane_b32 s5, v61, 63
	v_fmac_f32_e32 v44, s98, v125
	v_fmac_f32_e32 v46, s99, v125
	v_fmac_f32_e32 v44, s100, v126
	v_fmac_f32_e32 v46, s101, v126
	v_fmac_f32_e32 v44, s4, v127
	v_fmac_f32_e32 v46, s5, v127
	ds_write2st64_b32 v134, v44, v46 offset1:1
	s_waitcnt lgkmcnt(0)
	s_barrier
	s_and_saveexec_b64 s[4:5], vcc
	s_cbranch_execz .LBB0_22
	s_add_i32 s95, s93, 0x5f
	s_cmpk_gt_u32 s95, 0xbe
	v_mov_b32_e32 v0, 0
	s_cbranch_scc1 .LBB0_21
	s_mul_i32 s95, s94, 0xc00
	v_add_u32_e32 v0, s95, v36
	v_ashrrev_i32_e32 v1, 31, v0
	v_lshl_add_u64 v[0:1], v[0:1], 2, s[76:77]
	global_load_dword v0, v[0:1], off
	s_branch .LBB0_21
